# PA K-tile DMA issued one tile further ahead into free K region of ring slot; counted vmcnt(2) per tile
# speedup vs baseline: 1.0015x; 1.0015x over previous
; #define LAS __attribute__((address_space(3)))
; __device__ __forceinline__ void issue_tile(const bf16* Kg, const bf16* Vg, LAS unsigned char* slot, int kv0, int wave, int lane) {
;     const unsigned s0 = (unsigned)(uintptr_t)slot;
;     { const bf16* src = Kg + (size_t)(kv0 + lane) * 768 + wave * 8;
;       glds16(src, (unsigned)__builtin_amdgcn_readfirstlane(s0 + wave * 1024));
;       if (wave < 4) glds16(src + 64, (unsigned)__builtin_amdgcn_readfirstlane(s0 + (8 + wave) * 1024)); }
;     { const bf16* src = Vg + (size_t)(kv0 + 16 * (wave & 3) + (lane >> 2)) * 1024 + (wave >> 2) * 32 + (lane & 3) * 8;
;       glds16(src, (unsigned)__builtin_amdgcn_readfirstlane(s0 + KSLOT + wave * 1024)); }
; }
; __device__ __forceinline__ void attn_unit(const bf16* Q, const bf16* K, const bf16* V, bf16* O, int b, int h, int qb, float sref, LAS unsigned char* lds, int wave, int lane_) {
;     ...
;     issue_tile(Kg, Vg, lds, 0, wave, lane); issue_tile(Kg, Vg, lds + SLOT, 64, wave, lane);
.LBB0_1391:
	s_lshl_b64 s[16:17], s[16:17], 24
	s_add_u32 s8, s56, s16
	v_ashrrev_i32_e32 v24, 2, v159
	s_addc_u32 s9, s57, s17
	s_lshl_b32 s22, s1, 7
	v_add_u32_e32 v20, s61, v24
	s_add_u32 s34, s8, s22
	v_ashrrev_i32_e32 v21, 31, v20
	s_addc_u32 s35, s9, 0
	v_lshlrev_b64 v[20:21], 11, v[20:21]
	v_lshlrev_b32_e32 v18, 3, v159
	v_lshl_add_u64 v[22:23], s[34:35], 0, v[20:21]
	v_and_b32_e32 v25, 24, v18
	v_lshl_add_u64 v[22:23], s[18:19], 1, v[22:23]
	v_lshlrev_b32_e32 v18, 1, v25
	v_lshl_add_u64 v[22:23], v[22:23], 0, v[18:19]
	s_add_i32 s8, s60, 0x3000
	s_mov_b32 s9, m0
	s_mov_b32 m0, s8
	s_nop 0
	global_load_lds_dwordx4 v[22:23], off
	s_mov_b32 m0, s9
	v_add_u32_e32 v28, 64, v159
	v_mov_b64_e32 v[22:23], s[24:25]
	v_mad_i64_i32 v[22:23], s[48:49], v28, s65, v[22:23]
	v_lshl_add_u64 v[22:23], s[10:11], 1, v[22:23]
	s_mov_b64 s[98:99], 0x18000
	v_lshl_add_u64 v[226:227], v[22:23], 0, s[98:99]
	s_mov_b32 s9, m0
	s_mov_b32 m0, s62
	s_nop 0
	global_load_lds_dwordx4 v[22:23], off
	s_mov_b32 m0, s9
	s_and_b64 vcc, exec, s[2:3]
	s_cbranch_vccnz .LBB0_1393
	v_lshl_add_u64 v[22:23], v[22:23], 0, s[30:31]
	s_add_i32 s9, s62, 0x2000
	s_mov_b32 s22, m0
	s_mov_b32 m0, s9
	s_nop 0
	global_load_lds_dwordx4 v[22:23], off
	s_mov_b32 m0, s22
.LBB0_1393:
	v_add_u32_e32 v22, s63, v24
	v_ashrrev_i32_e32 v23, 31, v22
	v_lshlrev_b64 v[22:23], 11, v[22:23]
	v_lshl_add_u64 v[22:23], s[34:35], 0, v[22:23]
	v_lshl_add_u64 v[22:23], s[18:19], 1, v[22:23]
	v_lshl_add_u64 v[22:23], v[22:23], 0, v[18:19]
	s_add_i32 s9, s62, 0x3000
	s_mov_b32 s22, m0
	s_mov_b32 m0, s9
	s_nop 0
	global_load_lds_dwordx4 v[22:23], off
	s_mov_b32 m0, s22
	s_add_i32 s98, s62, 0x5000
	s_mov_b32 s99, m0
	s_mov_b32 m0, s98
	s_nop 0
	global_load_lds_dwordx4 v[226:227], off
	s_and_b64 vcc, exec, s[2:3]
	s_cbranch_vccnz .Lpa1_k2done
	v_lshl_add_u64 v[226:227], v[226:227], 0, s[30:31]
	s_add_i32 s98, s98, 0x2000
	s_mov_b32 m0, s98
	s_nop 0
	global_load_lds_dwordx4 v[226:227], off
.Lpa1_k2done:
	s_mov_b32 m0, s99
	s_mov_b64 s[48:49], -1
	s_and_b64 vcc, exec, s[14:15]
	s_cbranch_vccz .LBB0_1395
	s_waitcnt vmcnt(2)
	s_mov_b64 s[48:49], 0

; #define LAS __attribute__((address_space(3)))
; #define PA_BAR() do { asm volatile("s_waitcnt lgkmcnt(0)" ::: "memory"); __builtin_amdgcn_s_barrier(); asm volatile("" ::: "memory"); } while (0)
; __device__ __forceinline__ void issue_tile(const bf16* Kg, const bf16* Vg, LAS unsigned char* slot, int kv0, int wave, int lane) {
;     const unsigned s0 = (unsigned)(uintptr_t)slot;
;     { const bf16* src = Kg + (size_t)(kv0 + lane) * 768 + wave * 8;
;       glds16(src, (unsigned)__builtin_amdgcn_readfirstlane(s0 + wave * 1024));
;       if (wave < 4) glds16(src + 64, (unsigned)__builtin_amdgcn_readfirstlane(s0 + (8 + wave) * 1024)); }
;     { const bf16* src = Vg + (size_t)(kv0 + 16 * (wave & 3) + (lane >> 2)) * 1024 + (wave >> 2) * 32 + (lane & 3) * 8;
;       glds16(src, (unsigned)__builtin_amdgcn_readfirstlane(s0 + KSLOT + wave * 1024)); }
; }
; __device__ __forceinline__ void attn_unit(const bf16* Q, const bf16* K, const bf16* V, bf16* O, int b, int h, int qb, float sref, LAS unsigned char* lds, int wave, int lane_) {
;     ...
;     for (int t = 0; ; t += 2) {
;         const int s2 = (s1 == 2) ? 0 : s1 + 1;
;         asm volatile("s_waitcnt vmcnt(0)" ::: "memory"); PA_BAR();
;         if (t + 2 < NT) issue_tile(Kg, Vg, lds + s2 * SLOT, (t + 2) * 64, wave, lane);
.LBB0_1400:
	s_add_i32 s98, s72, -1
	s_cmp_lt_u32 s98, s73
	s_cbranch_scc1 .Lpa1_A_cnt
	s_waitcnt vmcnt(0)
	s_branch .Lpa1_A_join
.Lpa1_A_cnt:
	s_waitcnt vmcnt(2)
.Lpa1_A_join:
	s_add_i32 s22, s83, 1
	s_cmp_lg_u32 s83, 2
	s_cselect_b32 s75, s22, 0
	s_waitcnt lgkmcnt(0)
	s_barrier
	s_add_i32 s82, s72, -1
	s_cmp_lt_u32 s82, s73
	s_cselect_b64 s[52:53], -1, 0
	s_cmp_ge_u32 s82, s73
	s_mul_i32 s85, s75, 0x5000
	s_cbranch_scc1 .LBB0_1404
	v_add_u32_e32 v18, s74, v159
	s_add_i32 s22, s85, 0
	v_add_u32_e32 v18, 0xc0, v18
	v_mov_b64_e32 v[20:21], s[48:49]
	v_mad_i64_i32 v[20:21], s[86:87], v18, s65, v[20:21]
	s_add_i32 s22, s59, s22
	s_mul_i32 s98, s84, 0x5000
	s_add_i32 s98, s98, s59
	s_mov_b32 s86, m0
	s_mov_b32 m0, s98
	s_nop 0
	global_load_lds_dwordx4 v[20:21], off
	s_mov_b32 m0, s86
	s_and_b64 vcc, exec, s[2:3]
	s_cbranch_vccnz .LBB0_1403
	v_lshl_add_u64 v[20:21], v[20:21], 0, s[30:31]
	s_add_i32 s86, s98, 0x2000
	s_mov_b32 s87, m0
	s_mov_b32 m0, s86
	s_nop 0
	global_load_lds_dwordx4 v[20:21], off
	s_mov_b32 m0, s87

; #define PA_BAR() do { asm volatile("s_waitcnt lgkmcnt(0)" ::: "memory"); __builtin_amdgcn_s_barrier(); asm volatile("" ::: "memory"); } while (0)
; __device__ __forceinline__ void attn_unit(const bf16* Q, const bf16* K, const bf16* V, bf16* O, int b, int h, int qb, float sref, LAS unsigned char* lds, int wave, int lane_) {
;     ...
;         PA_SX(pB0, pB1, t + 1, s1, pA0, pA1); PA_PVN(pA0, pA1, sl);
;         asm volatile("s_waitcnt vmcnt(0)" ::: "memory"); PA_BAR();
.LBB0_1406:
	s_mul_i32 s86, s84, 0x5000
	s_add_i32 s86, s86, 0
	v_add_f32_e32 v170, v170, v18
	v_add_u32_e32 v18, s86, v172
	ds_read_b64_tr_b16 v[20:21], v18 offset:12288
	ds_read_b64_tr_b16 v[22:23], v18 offset:12800
	ds_read_b64_tr_b16 v[24:25], v18 offset:13312
	ds_read_b64_tr_b16 v[26:27], v18 offset:13824
	ds_read_b64_tr_b16 v[28:29], v18 offset:16384
	ds_read_b64_tr_b16 v[30:31], v18 offset:16896
	ds_read_b64_tr_b16 v[174:175], v18 offset:17408
	ds_read_b64_tr_b16 v[176:177], v18 offset:17920
	v_cvt_pk_bf16_f32 v178, v66, v67
	v_cvt_pk_bf16_f32 v179, v68, v69
	v_cvt_pk_bf16_f32 v180, v70, v71
	v_cvt_pk_bf16_f32 v181, v72, v73
	s_waitcnt lgkmcnt(6)
	v_mfma_f32_32x32x16_bf16 v[50:65], v[20:23], v[178:181], v[50:65]
	s_waitcnt lgkmcnt(2)
	v_mfma_f32_32x32x16_bf16 v[34:49], v[28:31], v[178:181], v[34:49]
	ds_read_b64_tr_b16 v[20:21], v18 offset:14336
	ds_read_b64_tr_b16 v[22:23], v18 offset:14848
	ds_read_b64_tr_b16 v[28:29], v18 offset:18432
	ds_read_b64_tr_b16 v[30:31], v18 offset:18944
	v_cvt_pk_bf16_f32 v178, v74, v75
	v_cvt_pk_bf16_f32 v179, v76, v77
	v_cvt_pk_bf16_f32 v180, v78, v79
	v_cvt_pk_bf16_f32 v181, v80, v81
	s_nop 0
	v_mfma_f32_32x32x16_bf16 v[50:65], v[24:27], v[178:181], v[50:65]
	s_waitcnt lgkmcnt(4)
	v_mfma_f32_32x32x16_bf16 v[34:49], v[174:177], v[178:181], v[34:49]
	ds_read_b64_tr_b16 v[24:25], v18 offset:15360
	ds_read_b64_tr_b16 v[26:27], v18 offset:15872
	ds_read_b64_tr_b16 v[174:175], v18 offset:19456
	ds_read_b64_tr_b16 v[176:177], v18 offset:19968
	v_cvt_pk_bf16_f32 v178, v82, v83
	v_cvt_pk_bf16_f32 v179, v84, v85
	v_cvt_pk_bf16_f32 v180, v86, v87
	v_cvt_pk_bf16_f32 v181, v88, v89
	s_waitcnt lgkmcnt(6)
	v_mfma_f32_32x32x16_bf16 v[50:65], v[20:23], v[178:181], v[50:65]
	s_waitcnt lgkmcnt(4)
	v_mfma_f32_32x32x16_bf16 v[34:49], v[28:31], v[178:181], v[34:49]
	v_cvt_pk_bf16_f32 v20, v90, v91
	v_cvt_pk_bf16_f32 v21, v92, v93
	v_cvt_pk_bf16_f32 v22, v94, v95
	v_cvt_pk_bf16_f32 v23, v96, v97
	s_waitcnt lgkmcnt(2)
	v_mfma_f32_32x32x16_bf16 v[50:65], v[24:27], v[20:23], v[50:65]
	s_waitcnt lgkmcnt(0)
	v_mfma_f32_32x32x16_bf16 v[34:49], v[174:177], v[20:23], v[34:49]
	s_and_b64 vcc, exec, s[52:53]
	s_cbranch_vccz .Lpa1_B_full
	s_waitcnt vmcnt(2)
	s_branch .Lpa1_B_join

; #define LAS __attribute__((address_space(3)))
; #define PA_BAR() do { asm volatile("s_waitcnt lgkmcnt(0)" ::: "memory"); __builtin_amdgcn_s_barrier(); asm volatile("" ::: "memory"); } while (0)
; __device__ __forceinline__ void issue_tile(const bf16* Kg, const bf16* Vg, LAS unsigned char* slot, int kv0, int wave, int lane) {
;     const unsigned s0 = (unsigned)(uintptr_t)slot;
;     { const bf16* src = Kg + (size_t)(kv0 + lane) * 768 + wave * 8;
;       glds16(src, (unsigned)__builtin_amdgcn_readfirstlane(s0 + wave * 1024));
;       if (wave < 4) glds16(src + 64, (unsigned)__builtin_amdgcn_readfirstlane(s0 + (8 + wave) * 1024)); }
;     { const bf16* src = Vg + (size_t)(kv0 + 16 * (wave & 3) + (lane >> 2)) * 1024 + (wave >> 2) * 32 + (lane & 3) * 8;
;       glds16(src, (unsigned)__builtin_amdgcn_readfirstlane(s0 + KSLOT + wave * 1024)); }
; }
; __device__ __forceinline__ void attn_unit(const bf16* Q, const bf16* K, const bf16* V, bf16* O, int b, int h, int qb, float sref, LAS unsigned char* lds, int wave, int lane_) {
;     ...
;         asm volatile("s_waitcnt vmcnt(0)" ::: "memory"); PA_BAR();
;         if (t + 2 >= NT) break;
;         if (t + 3 < NT) issue_tile(Kg, Vg, lds + sl * SLOT, (t + 3) * 64, wave, lane);
.Lpa1_B_join:
	s_waitcnt lgkmcnt(0)
	s_barrier
	s_andn2_b64 vcc, exec, s[52:53]
	s_cbranch_vccnz .LBB0_1414
	s_cmp_ge_u32 s72, s73
	s_cbranch_scc1 .LBB0_1411
	v_add_u32_e32 v18, s74, v159
	v_add_u32_e32 v18, 0x100, v18
	v_mov_b64_e32 v[20:21], s[48:49]
	v_mad_i64_i32 v[20:21], s[52:53], v18, s65, v[20:21]
	s_add_i32 s52, s59, s86
	s_add_i32 s98, s72, 1
	s_cmp_ge_u32 s98, s73
	s_cbranch_scc1 .Lpa1_noK
	s_add_i32 s98, s59, s22
	s_mov_b32 s53, m0
	s_mov_b32 m0, s98
	s_nop 0
	global_load_lds_dwordx4 v[20:21], off
	s_mov_b32 m0, s53
	s_and_b64 vcc, exec, s[2:3]
	s_cbranch_vccnz .LBB0_1410
	v_lshl_add_u64 v[20:21], v[20:21], 0, s[30:31]
	s_add_i32 s53, s98, 0x2000
	s_mov_b32 s83, m0
	s_mov_b32 m0, s53
	s_nop 0
	global_load_lds_dwordx4 v[20:21], off
	s_mov_b32 m0, s83
.Lpa1_noK:
.LBB0_1410:
	s_addk_i32 s52, 0x3000
	s_mov_b32 s53, m0
	s_mov_b32 m0, s52
	s_nop 0
	global_load_lds_dwordx4 v[160:161], off
	s_mov_b32 m0, s53

; #define LAS __attribute__((address_space(3)))
; __device__ __forceinline__ void issue_tile(const bf16* Kg, const bf16* Vg, LAS unsigned char* slot, int kv0, int wave, int lane) {
;     const unsigned s0 = (unsigned)(uintptr_t)slot;
;     { const bf16* src = Kg + (size_t)(kv0 + lane) * 768 + wave * 8;
;       glds16(src, (unsigned)__builtin_amdgcn_readfirstlane(s0 + wave * 1024));
;       if (wave < 4) glds16(src + 64, (unsigned)__builtin_amdgcn_readfirstlane(s0 + (8 + wave) * 1024)); }
;     { const bf16* src = Vg + (size_t)(kv0 + 16 * (wave & 3) + (lane >> 2)) * 1024 + (wave >> 2) * 32 + (lane & 3) * 8;
;       glds16(src, (unsigned)__builtin_amdgcn_readfirstlane(s0 + KSLOT + wave * 1024)); }
; }
; __device__ __forceinline__ void attn_unit(const bf16* Q, const bf16* K, const bf16* V, bf16* O, int b, int h, int qb, float sref, LAS unsigned char* lds, int wave, int lane_) {
;     ...
;     issue_tile(Kg, Vg, lds, 0, wave, lane); issue_tile(Kg, Vg, lds + SLOT, 64, wave, lane);
.LBB0_1419:
	v_ashrrev_i32_e32 v24, 2, v159
	v_add_u32_e32 v20, s61, v24
	v_ashrrev_i32_e32 v21, 31, v20
	v_lshlrev_b64 v[20:21], 11, v[20:21]
	v_lshlrev_b32_e32 v18, 3, v159
	v_lshl_add_u64 v[22:23], s[34:35], 0, v[20:21]
	v_and_b32_e32 v25, 24, v18
	v_lshl_add_u64 v[22:23], s[18:19], 1, v[22:23]
	v_lshlrev_b32_e32 v18, 1, v25
	v_lshl_add_u64 v[22:23], v[22:23], 0, v[18:19]
	s_mov_b32 s12, m0
	s_mov_b32 m0, s8
	s_nop 0
	global_load_lds_dwordx4 v[22:23], off
	s_mov_b32 m0, s12
	v_add_u32_e32 v28, 64, v159
	v_mov_b64_e32 v[22:23], s[24:25]
	v_mad_i64_i32 v[22:23], s[24:25], v28, s65, v[22:23]
	v_lshl_add_u64 v[22:23], s[10:11], 1, v[22:23]
	s_mov_b64 s[98:99], 0x18000
	v_lshl_add_u64 v[226:227], v[22:23], 0, s[98:99]
	s_mov_b32 s8, m0
	s_mov_b32 m0, s62
	s_nop 0
	global_load_lds_dwordx4 v[22:23], off
	s_mov_b32 m0, s8
	s_and_b64 vcc, exec, s[2:3]
	s_cbranch_vccnz .LBB0_1421
	v_lshl_add_u64 v[22:23], v[22:23], 0, s[30:31]
	s_add_i32 s8, s62, 0x2000
	s_mov_b32 s12, m0
	s_mov_b32 m0, s8
	s_nop 0
	global_load_lds_dwordx4 v[22:23], off
	s_mov_b32 m0, s12
.LBB0_1421:
	v_add_u32_e32 v22, s63, v24
	v_ashrrev_i32_e32 v23, 31, v22
	v_lshlrev_b64 v[22:23], 11, v[22:23]
	v_lshl_add_u64 v[22:23], s[34:35], 0, v[22:23]
	v_lshl_add_u64 v[22:23], s[18:19], 1, v[22:23]
	v_lshl_add_u64 v[22:23], v[22:23], 0, v[18:19]
	s_mov_b32 s8, m0
	s_mov_b32 m0, s9
	s_nop 0
	global_load_lds_dwordx4 v[22:23], off
	s_mov_b32 m0, s8
	s_add_i32 s98, s62, 0x5000
	s_mov_b32 s99, m0
	s_mov_b32 m0, s98
	s_nop 0
	global_load_lds_dwordx4 v[226:227], off
	s_and_b64 vcc, exec, s[2:3]
	s_cbranch_vccnz .Lpa2_k2done
	v_lshl_add_u64 v[226:227], v[226:227], 0, s[30:31]
	s_add_i32 s98, s98, 0x2000
	s_mov_b32 m0, s98
	s_nop 0
	global_load_lds_dwordx4 v[226:227], off
.Lpa2_k2done:
	s_mov_b32 m0, s99
	s_mov_b64 s[24:25], -1
	s_and_b64 vcc, exec, s[14:15]
	s_cbranch_vccz .LBB0_1423
	s_waitcnt vmcnt(2)
	s_mov_b64 s[24:25], 0

; #define PA_BAR() do { asm volatile("s_waitcnt lgkmcnt(0)" ::: "memory"); __builtin_amdgcn_s_barrier(); asm volatile("" ::: "memory"); } while (0)
; __device__ __forceinline__ void attn_unit(const bf16* Q, const bf16* K, const bf16* V, bf16* O, int b, int h, int qb, float sref, LAS unsigned char* lds, int wave, int lane_) {
;     ...
;     for (int t = 0; ; t += 2) {
;         const int s2 = (s1 == 2) ? 0 : s1 + 1;
;         asm volatile("s_waitcnt vmcnt(0)" ::: "memory"); PA_BAR();
.LBB0_1428:
	s_add_i32 s98, s8, -1
	s_cmp_lt_u32 s98, s9
	s_cbranch_scc1 .Lpa2_A_cnt
	s_waitcnt vmcnt(0)
	s_branch .Lpa2_A_join

; #define LAS __attribute__((address_space(3)))
; #define PA_BAR() do { asm volatile("s_waitcnt lgkmcnt(0)" ::: "memory"); __builtin_amdgcn_s_barrier(); asm volatile("" ::: "memory"); } while (0)
; __device__ __forceinline__ void issue_tile(const bf16* Kg, const bf16* Vg, LAS unsigned char* slot, int kv0, int wave, int lane) {
;     const unsigned s0 = (unsigned)(uintptr_t)slot;
;     { const bf16* src = Kg + (size_t)(kv0 + lane) * 768 + wave * 8;
;       glds16(src, (unsigned)__builtin_amdgcn_readfirstlane(s0 + wave * 1024));
;       if (wave < 4) glds16(src + 64, (unsigned)__builtin_amdgcn_readfirstlane(s0 + (8 + wave) * 1024)); }
;     { const bf16* src = Vg + (size_t)(kv0 + 16 * (wave & 3) + (lane >> 2)) * 1024 + (wave >> 2) * 32 + (lane & 3) * 8;
;       glds16(src, (unsigned)__builtin_amdgcn_readfirstlane(s0 + KSLOT + wave * 1024)); }
; }
; __device__ __forceinline__ void attn_unit(const bf16* Q, const bf16* K, const bf16* V, bf16* O, int b, int h, int qb, float sref, LAS unsigned char* lds, int wave, int lane_) {
;     ...
;     for (int t = 0; ; t += 2) {
;         const int s2 = (s1 == 2) ? 0 : s1 + 1;
;         asm volatile("s_waitcnt vmcnt(0)" ::: "memory"); PA_BAR();
;         if (t + 2 < NT) issue_tile(Kg, Vg, lds + s2 * SLOT, (t + 2) * 64, wave, lane);
.Lpa2_A_join:
	s_add_i32 s12, s25, 1
	s_cmp_lg_u32 s25, 2
	s_cselect_b32 s12, s12, 0
	s_waitcnt lgkmcnt(0)
	s_barrier
	s_add_i32 s24, s8, -1
	s_cmp_lt_u32 s24, s9
	s_cselect_b64 s[16:17], -1, 0
	s_cmp_ge_u32 s24, s9
	s_mul_i32 s27, s12, 0x5000
	s_cbranch_scc1 .LBB0_1432
	v_add_u32_e32 v18, s1, v159
	s_add_i32 s22, s27, 0
	v_add_u32_e32 v18, 0xc0, v18
	v_mov_b64_e32 v[20:21], s[48:49]
	v_mad_i64_i32 v[20:21], s[34:35], v18, s65, v[20:21]
	s_add_i32 s22, s59, s22
	s_mul_i32 s98, s26, 0x5000
	s_add_i32 s98, s98, s59
	s_mov_b32 s33, m0
	s_mov_b32 m0, s98
	s_nop 0
	global_load_lds_dwordx4 v[20:21], off
	s_mov_b32 m0, s33
	s_and_b64 vcc, exec, s[2:3]
	s_cbranch_vccnz .LBB0_1431
	v_lshl_add_u64 v[20:21], v[20:21], 0, s[30:31]
	s_add_i32 s33, s98, 0x2000
	s_mov_b32 s34, m0
	s_mov_b32 m0, s33
	s_nop 0
	global_load_lds_dwordx4 v[20:21], off
	s_mov_b32 m0, s34

; #define PA_BAR() do { asm volatile("s_waitcnt lgkmcnt(0)" ::: "memory"); __builtin_amdgcn_s_barrier(); asm volatile("" ::: "memory"); } while (0)
; __device__ __forceinline__ void attn_unit(const bf16* Q, const bf16* K, const bf16* V, bf16* O, int b, int h, int qb, float sref, LAS unsigned char* lds, int wave, int lane_) {
;     ...
;         PA_SX(pB0, pB1, t + 1, s1, pA0, pA1); PA_PVN(pA0, pA1, sl);
;         asm volatile("s_waitcnt vmcnt(0)" ::: "memory"); PA_BAR();
.LBB0_1434:
	s_mul_i32 s33, s26, 0x5000
	s_add_i32 s33, s33, 0
	v_add_f32_e32 v170, v170, v18
	v_add_u32_e32 v18, s33, v172
	ds_read_b64_tr_b16 v[20:21], v18 offset:12288
	ds_read_b64_tr_b16 v[22:23], v18 offset:12800
	ds_read_b64_tr_b16 v[24:25], v18 offset:13312
	ds_read_b64_tr_b16 v[26:27], v18 offset:13824
	ds_read_b64_tr_b16 v[28:29], v18 offset:16384
	ds_read_b64_tr_b16 v[30:31], v18 offset:16896
	ds_read_b64_tr_b16 v[174:175], v18 offset:17408
	ds_read_b64_tr_b16 v[176:177], v18 offset:17920
	v_cvt_pk_bf16_f32 v178, v66, v67
	v_cvt_pk_bf16_f32 v179, v68, v69
	v_cvt_pk_bf16_f32 v180, v70, v71
	v_cvt_pk_bf16_f32 v181, v72, v73
	s_waitcnt lgkmcnt(6)
	v_mfma_f32_32x32x16_bf16 v[50:65], v[20:23], v[178:181], v[50:65]
	s_waitcnt lgkmcnt(2)
	v_mfma_f32_32x32x16_bf16 v[34:49], v[28:31], v[178:181], v[34:49]
	ds_read_b64_tr_b16 v[20:21], v18 offset:14336
	ds_read_b64_tr_b16 v[22:23], v18 offset:14848
	ds_read_b64_tr_b16 v[28:29], v18 offset:18432
	ds_read_b64_tr_b16 v[30:31], v18 offset:18944
	v_cvt_pk_bf16_f32 v178, v74, v75
	v_cvt_pk_bf16_f32 v179, v76, v77
	v_cvt_pk_bf16_f32 v180, v78, v79
	v_cvt_pk_bf16_f32 v181, v80, v81
	s_nop 0
	v_mfma_f32_32x32x16_bf16 v[50:65], v[24:27], v[178:181], v[50:65]
	s_waitcnt lgkmcnt(4)
	v_mfma_f32_32x32x16_bf16 v[34:49], v[174:177], v[178:181], v[34:49]
	ds_read_b64_tr_b16 v[24:25], v18 offset:15360
	ds_read_b64_tr_b16 v[26:27], v18 offset:15872
	ds_read_b64_tr_b16 v[174:175], v18 offset:19456
	ds_read_b64_tr_b16 v[176:177], v18 offset:19968
	v_cvt_pk_bf16_f32 v178, v82, v83
	v_cvt_pk_bf16_f32 v179, v84, v85
	v_cvt_pk_bf16_f32 v180, v86, v87
	v_cvt_pk_bf16_f32 v181, v88, v89
	s_waitcnt lgkmcnt(6)
	v_mfma_f32_32x32x16_bf16 v[50:65], v[20:23], v[178:181], v[50:65]
	s_waitcnt lgkmcnt(4)
	v_mfma_f32_32x32x16_bf16 v[34:49], v[28:31], v[178:181], v[34:49]
	v_cvt_pk_bf16_f32 v20, v90, v91
	v_cvt_pk_bf16_f32 v21, v92, v93
	v_cvt_pk_bf16_f32 v22, v94, v95
	v_cvt_pk_bf16_f32 v23, v96, v97
	s_waitcnt lgkmcnt(2)
	v_mfma_f32_32x32x16_bf16 v[50:65], v[24:27], v[20:23], v[50:65]
	s_waitcnt lgkmcnt(0)
	v_mfma_f32_32x32x16_bf16 v[34:49], v[174:177], v[20:23], v[34:49]
	s_and_b64 vcc, exec, s[16:17]
	s_cbranch_vccz .Lpa2_B_full
	s_waitcnt vmcnt(2)
	s_branch .Lpa2_B_join

; #define LAS __attribute__((address_space(3)))
; #define PA_BAR() do { asm volatile("s_waitcnt lgkmcnt(0)" ::: "memory"); __builtin_amdgcn_s_barrier(); asm volatile("" ::: "memory"); } while (0)
; __device__ __forceinline__ void issue_tile(const bf16* Kg, const bf16* Vg, LAS unsigned char* slot, int kv0, int wave, int lane) {
;     const unsigned s0 = (unsigned)(uintptr_t)slot;
;     { const bf16* src = Kg + (size_t)(kv0 + lane) * 768 + wave * 8;
;       glds16(src, (unsigned)__builtin_amdgcn_readfirstlane(s0 + wave * 1024));
;       if (wave < 4) glds16(src + 64, (unsigned)__builtin_amdgcn_readfirstlane(s0 + (8 + wave) * 1024)); }
;     { const bf16* src = Vg + (size_t)(kv0 + 16 * (wave & 3) + (lane >> 2)) * 1024 + (wave >> 2) * 32 + (lane & 3) * 8;
;       glds16(src, (unsigned)__builtin_amdgcn_readfirstlane(s0 + KSLOT + wave * 1024)); }
; }
; __device__ __forceinline__ void attn_unit(const bf16* Q, const bf16* K, const bf16* V, bf16* O, int b, int h, int qb, float sref, LAS unsigned char* lds, int wave, int lane_) {
;     ...
;         asm volatile("s_waitcnt vmcnt(0)" ::: "memory"); PA_BAR();
;         if (t + 2 >= NT) break;
;         if (t + 3 < NT) issue_tile(Kg, Vg, lds + sl * SLOT, (t + 3) * 64, wave, lane);
.Lpa2_B_join:
	s_waitcnt lgkmcnt(0)
	s_barrier
	s_andn2_b64 vcc, exec, s[16:17]
	s_cbranch_vccnz .LBB0_1442
	s_cmp_ge_u32 s8, s9
	s_cbranch_scc1 .LBB0_1439
	v_add_u32_e32 v18, s1, v159
	v_add_u32_e32 v18, 0x100, v18
	v_mov_b64_e32 v[20:21], s[48:49]
	v_mad_i64_i32 v[20:21], s[16:17], v18, s65, v[20:21]
	s_add_i32 s16, s59, s33
	s_add_i32 s98, s8, 1
	s_cmp_ge_u32 s98, s9
	s_cbranch_scc1 .Lpa2_noK
	s_add_i32 s98, s59, s22
	s_mov_b32 s17, m0
	s_mov_b32 m0, s98
	s_nop 0
	global_load_lds_dwordx4 v[20:21], off
	s_mov_b32 m0, s17
	s_and_b64 vcc, exec, s[2:3]
	s_cbranch_vccnz .LBB0_1438
	v_lshl_add_u64 v[20:21], v[20:21], 0, s[30:31]
	s_add_i32 s17, s98, 0x2000
	s_mov_b32 s25, m0
	s_mov_b32 m0, s17
	s_nop 0
	global_load_lds_dwordx4 v[20:21], off
	s_mov_b32 m0, s25
.Lpa2_noK:
.LBB0_1438:
	s_addk_i32 s16, 0x3000
	s_mov_b32 s17, m0
	s_mov_b32 m0, s16
	s_nop 0
	global_load_lds_dwordx4 v[160:161], off
	s_mov_b32 m0, s17

; __global__ void __launch_bounds__(NWAVES * 64, 2) mk_fwd(Args args) {
	.amdhsa_kernel _Z6mk_fwd4Args
		.amdhsa_group_segment_fixed_size 0
		.amdhsa_private_segment_fixed_size 0
		.amdhsa_kernarg_size 592
		.amdhsa_user_sgpr_count 2
		.amdhsa_user_sgpr_dispatch_ptr 0
		.amdhsa_user_sgpr_queue_ptr 0
		.amdhsa_user_sgpr_kernarg_segment_ptr 1
		.amdhsa_user_sgpr_dispatch_id 0
		.amdhsa_user_sgpr_kernarg_preload_length 0
		.amdhsa_user_sgpr_kernarg_preload_offset 0
		.amdhsa_user_sgpr_private_segment_size 0
		.amdhsa_uses_dynamic_stack 0
		.amdhsa_enable_private_segment 0
		.amdhsa_system_sgpr_workgroup_id_x 1
		.amdhsa_system_sgpr_workgroup_id_y 0
		.amdhsa_system_sgpr_workgroup_id_z 0
		.amdhsa_system_sgpr_workgroup_info 0
		.amdhsa_system_vgpr_workitem_id 0
		.amdhsa_next_free_vgpr 256
		.amdhsa_next_free_sgpr 100
		.amdhsa_accum_offset 256
		.amdhsa_reserve_vcc 1
		.amdhsa_float_round_mode_32 0
		.amdhsa_float_round_mode_16_64 0
		.amdhsa_float_denorm_mode_32 3
		.amdhsa_float_denorm_mode_16_64 3
		.amdhsa_dx10_clamp 1
		.amdhsa_ieee_mode 1
		.amdhsa_fp16_overflow 0
		.amdhsa_tg_split 0
		.amdhsa_exception_fp_ieee_invalid_op 0
		.amdhsa_exception_fp_denorm_src 0
		.amdhsa_exception_fp_ieee_div_zero 0
		.amdhsa_exception_fp_ieee_overflow 0
		.amdhsa_exception_fp_ieee_underflow 0
		.amdhsa_exception_fp_ieee_inexact 0
		.amdhsa_exception_int_div_zero 0
	.end_amdhsa_kernel

; __global__ void __launch_bounds__(NWAVES * 64, 2) mk_fwd(Args args) {
amdhsa.kernels:
  - .agpr_count:     0
    .args:
      - .offset:         0
        .size:           336
        .value_kind:     by_value
      - .offset:         336
        .size:           4
        .value_kind:     hidden_block_count_x
      - .offset:         340
        .size:           4
        .value_kind:     hidden_block_count_y
      - .offset:         344
        .size:           4
        .value_kind:     hidden_block_count_z
      - .offset:         348
        .size:           2
        .value_kind:     hidden_group_size_x
      - .offset:         350
        .size:           2
        .value_kind:     hidden_group_size_y
      - .offset:         352
        .size:           2
        .value_kind:     hidden_group_size_z
      - .offset:         354
        .size:           2
        .value_kind:     hidden_remainder_x
      - .offset:         356
        .size:           2
        .value_kind:     hidden_remainder_y
      - .offset:         358
        .size:           2
        .value_kind:     hidden_remainder_z
      - .offset:         376
        .size:           8
        .value_kind:     hidden_global_offset_x
      - .offset:         384
        .size:           8
        .value_kind:     hidden_global_offset_y
      - .offset:         392
        .size:           8
        .value_kind:     hidden_global_offset_z
      - .offset:         400
        .size:           2
        .value_kind:     hidden_grid_dims
      - .offset:         456
        .size:           4
        .value_kind:     hidden_dynamic_lds_size
    .group_segment_fixed_size: 0
    .kernarg_segment_align: 8
    .kernarg_segment_size: 592
    .language:       OpenCL C
    .language_version:
      - 2
      - 0
    .max_flat_workgroup_size: 512
    .name:           _Z6mk_fwd4Args
    .private_segment_fixed_size: 0
    .sgpr_count:     106
    .sgpr_spill_count: 132
    .symbol:         _Z6mk_fwd4Args.kd
    .uniform_work_group_size: 1
    .uses_dynamic_stack: false
    .vgpr_count:     256
    .vgpr_spill_count: 0
    .wavefront_size: 64
